# mixers: conformer loop start rotated by 128 blocks and pool loop by 64, so the three 8-tile tails land on three different block groups
# baseline (speedup 1.0000x reference)
; #define LAS __attribute__((address_space(3)))
; DI float bf2f(bf16_t v) { return __uint_as_float(((unsigned)v) << 16); }
; DI float bflo(unsigned v) { return __uint_as_float(v << 16); }
; DI float bfhi(unsigned v) { return __uint_as_float(v & 0xffff0000u); }
; DI unsigned pk2(float lo, float hi) { f32x2 v = {lo, hi}; bf2_t r = __builtin_convertvector(v, bf2_t); return __builtin_bit_cast(unsigned, r); }
; DI void phase_mixers(const Params& p, int l, LAS char* lds) {
;     ...
;     for (int tile = vblock(); tile < 8 * 129; tile += gridDim.x) {
;         const int b = tile / 129, t0 = (tile - b * 129) * 32;
;         const bf16_t* zb = zc + (size_t)b * LSEQ * 2304;
;         bf16_t* ub = u + (size_t)b * LSEQ * 1280;
;         {
;             asm volatile("" ::: "memory");
;             LAS bf16_t* gl = (LAS bf16_t*)(lds + 32768);
;             {
;                 u32x4 av[8], gv[8];
; #pragma unroll
;                 for (int it = 0; it < 8; ++it) {
;                     const int q = c + 256 * it, r = q >> 5, c8 = (q & 31) * 8, t = t0 - 30 + r;
;                     av[it] = (u32x4){0u, 0u, 0u, 0u}; gv[it] = (u32x4){0u, 0u, 0u, 0u};
;                     if (q < 62 * 32 && t >= 0 && t < LSEQ) { const bf16_t* rp = zb + (size_t)t * 2304; av[it] = *(const u32x4*)(rp + 512 + c8); gv[it] = *(const u32x4*)(rp + 768 + c8); }
;                 }
; #pragma unroll
;                 for (int it = 0; it < 8; ++it) {
;                     const int q = c + 256 * it, r = q >> 5, c8 = (q & 31) * 8;
;                     u32x4 o;
; #pragma unroll
;                     for (int e = 0; e < 4; ++e) o[e] = pk2(bflo(av[it][e]) * sigm(bflo(gv[it][e])), bfhi(av[it][e]) * sigm(bfhi(gv[it][e])));
;                     if (q < 62 * 32) *(LAS u32x4*)(gl + r * 256 + c8) = o;
;                 }
;             }
;             __syncthreads();
;             {
;                 float wk[31];
; #pragma unroll
;                 for (int k = 0; k < 31; ++k) wk[k] = cw[k * 256 + c];
;                 const float bias = p.conf_dw_b[l * 256 + c];
;                 float g[62];
; #pragma unroll
;                 for (int i = 0; i < 62; ++i) g[i] = bf2f(gl[i * 256 + c]);
; #pragma unroll
;                 for (int tt = 0; tt < 32; ++tt) {
;                     float y = bias;
; #pragma unroll
;                     for (int k = 0; k < 31; ++k) y += wk[k] * g[tt + k];
.LBB0_175:
	s_add_i32 s63, s63, s3
	s_add_i32 s63, s63, 0xffffff80
	s_add_i32 s64, s3, -1
	s_and_b32 s63, s63, s64
	v_readlane_b32 s0, v228, 30
	s_lshl_b32 s40, s0, 8
	v_add_u32_e32 v66, s40, v102
	v_lshlrev_b32_e32 v1, 1, v102
	v_add_u32_e32 v2, 0x100, v102
	v_add_u32_e32 v3, 0x200, v102
	v_add_u32_e32 v4, 0x300, v102
	v_add_u32_e32 v5, 0x400, v102
	v_add_u32_e32 v6, 0x500, v102
	s_cmpk_gt_i32 s63, 0x407
	v_ashrrev_i32_e32 v99, 5, v102
	v_lshlrev_b32_e32 v138, 4, v102
	v_ashrrev_i32_e32 v103, 31, v102
	v_ashrrev_i32_e32 v67, 31, v66
	v_ashrrev_i32_e32 v178, 5, v2
	v_ashrrev_i32_e32 v179, 5, v3
	v_ashrrev_i32_e32 v180, 5, v4
	v_ashrrev_i32_e32 v181, 5, v5
	v_ashrrev_i32_e32 v182, 5, v6
	v_lshlrev_b32_e32 v140, 4, v2
	v_lshlrev_b32_e32 v141, 4, v3
	v_lshlrev_b32_e32 v142, 4, v4
	v_lshlrev_b32_e32 v143, 4, v5
	v_lshlrev_b32_e32 v139, 4, v6
	v_add_u32_e32 v183, v1, v1
	s_cbranch_scc1 .LBB0_226
	v_readlane_b32 s0, v228, 30
	s_mulk_i32 s0, 0x1f00
	s_ashr_i32 s1, s0, 31
	v_readlane_b32 s44, v231, 51
	s_lshl_b64 s[0:1], s[0:1], 2
	v_readlane_b32 s54, v231, 61
	v_readlane_b32 s55, v231, 62
	s_add_u32 s0, s54, s0
	s_addc_u32 s1, s55, s1
	v_add_u32_e32 v3, 0x600, v102
	v_lshl_add_u64 v[68:69], v[102:103], 2, s[0:1]
	v_lshlrev_b32_e32 v2, 1, v98
	v_ashrrev_i32_e32 v4, 5, v3
	v_add_u32_e32 v5, 0x700, v102
	s_movk_i32 s0, 0xfe00
	v_lshlrev_b32_e32 v3, 4, v3
	v_and_or_b32 v155, v3, s0, v2
	v_lshlrev_b32_e32 v3, 4, v5
	v_and_or_b32 v145, v138, s0, v2
	v_and_or_b32 v146, v140, s0, v2
	v_and_or_b32 v147, v141, s0, v2
	v_and_or_b32 v152, v142, s0, v2
	v_and_or_b32 v153, v143, s0, v2
	v_and_or_b32 v154, v139, s0, v2
	v_and_or_b32 v156, v3, s0, v2
	s_mov_b64 s[0:1], 0x1000
	v_lshl_add_u64 v[74:75], v[68:69], 0, s[0:1]
	s_mov_b64 s[0:1], 0x1400
	v_lshl_add_u64 v[76:77], v[68:69], 0, s[0:1]
	s_mov_b64 s[0:1], 0x1800
	v_lshl_add_u64 v[78:79], v[68:69], 0, s[0:1]
	s_mov_b64 s[0:1], 0x1c00
	v_lshl_add_u64 v[80:81], v[68:69], 0, s[0:1]
	s_mov_b64 s[0:1], 0x2000
	v_lshl_add_u64 v[82:83], v[68:69], 0, s[0:1]
	s_mov_b64 s[0:1], 0x2400
	v_lshl_add_u64 v[84:85], v[68:69], 0, s[0:1]
	s_mov_b64 s[0:1], 0x2800
	v_lshl_add_u64 v[86:87], v[68:69], 0, s[0:1]
	s_mov_b64 s[0:1], 0x2c00
	v_lshl_add_u64 v[88:89], v[68:69], 0, s[0:1]
	s_mov_b64 s[0:1], 0x3000
	v_lshl_add_u64 v[90:91], v[68:69], 0, s[0:1]
	s_mov_b64 s[0:1], 0x3400
	v_lshl_add_u64 v[92:93], v[68:69], 0, s[0:1]
	s_mov_b64 s[0:1], 0x3800
	v_lshl_add_u64 v[94:95], v[68:69], 0, s[0:1]
	s_mov_b64 s[0:1], 0x3c00
	v_lshl_add_u64 v[96:97], v[68:69], 0, s[0:1]
	s_mov_b64 s[0:1], 0x4000
	v_lshl_add_u64 v[104:105], v[68:69], 0, s[0:1]
	s_mov_b64 s[0:1], 0x4400
	v_lshl_add_u64 v[106:107], v[68:69], 0, s[0:1]
	s_mov_b64 s[0:1], 0x4800
	v_lshl_add_u64 v[108:109], v[68:69], 0, s[0:1]
	s_mov_b64 s[0:1], 0x4c00
	v_lshl_add_u64 v[110:111], v[68:69], 0, s[0:1]
	s_mov_b64 s[0:1], 0x5000
	v_lshl_add_u64 v[112:113], v[68:69], 0, s[0:1]
	s_mov_b64 s[0:1], 0x5400
	v_lshlrev_b32_e32 v148, 4, v114
	v_lshl_add_u64 v[114:115], v[68:69], 0, s[0:1]
	s_mov_b64 s[0:1], 0x5800
	v_lshl_add_u64 v[116:117], v[68:69], 0, s[0:1]
	s_mov_b64 s[0:1], 0x5c00
	v_lshl_add_u64 v[118:119], v[68:69], 0, s[0:1]
	s_mov_b64 s[0:1], 0x6000
	v_lshl_add_u64 v[120:121], v[68:69], 0, s[0:1]
	s_mov_b64 s[0:1], 0x6400
	v_lshl_add_u64 v[122:123], v[68:69], 0, s[0:1]
	s_mov_b64 s[0:1], 0x6800
	v_lshl_add_u64 v[124:125], v[68:69], 0, s[0:1]
	s_mov_b64 s[0:1], 0x6c00
	v_lshl_add_u64 v[126:127], v[68:69], 0, s[0:1]
	s_mov_b64 s[0:1], 0x7000
	v_lshl_add_u64 v[128:129], v[68:69], 0, s[0:1]
	s_mov_b64 s[0:1], 0x7400
	v_lshl_add_u64 v[130:131], v[68:69], 0, s[0:1]
	s_mov_b64 s[0:1], 0x7800
	v_ashrrev_i32_e32 v6, 5, v5
	v_lshl_add_u64 v[132:133], v[68:69], 0, s[0:1]
	s_movk_i32 s0, 0x900
	v_mul_lo_u32 v3, v6, s0
	v_add_u32_e32 v157, 0xfffef200, v3
	v_mul_lo_u32 v3, v4, s0
	v_add_u32_e32 v159, 0xfffef200, v3
	v_mul_lo_u32 v3, v182, s0
	v_add_u32_e32 v161, 0xfffef200, v3
	v_mul_lo_u32 v3, v181, s0
	v_add_u32_e32 v185, 0xfffef200, v3
	v_mul_lo_u32 v3, v180, s0
	v_add_u32_e32 v187, 0xfffef200, v3
	v_mul_lo_u32 v3, v179, s0
	v_add_u32_e32 v189, 0xfffef200, v3
	v_mul_lo_u32 v3, v178, s0
	v_add_u32_e32 v191, 0xfffef200, v3
	v_mul_lo_u32 v3, v99, s0
	s_movk_i32 s0, 0x7c0
	s_ashr_i32 s41, s40, 31
	v_cmp_gt_i32_e32 vcc, s0, v102
	s_movk_i32 s0, 0x6c0
	s_lshl_b64 s[4:5], s[40:41], 2
	v_cmp_gt_i32_e64 s[40:41], s0, v102
	s_movk_i32 s0, 0x5c0
	v_readlane_b32 s45, v231, 52
	v_readlane_b32 s58, v230, 1
	v_cmp_gt_i32_e64 s[42:43], s0, v102
	s_movk_i32 s0, 0x4c0
	v_readlane_b32 s46, v231, 53
	v_readlane_b32 s47, v231, 54
	v_readlane_b32 s59, v230, 2
	s_add_u32 s6, s58, s4
	v_cmp_gt_i32_e64 s[44:45], s0, v102
	s_movk_i32 s0, 0x3c0
	v_readlane_b32 s48, v231, 55
	v_readlane_b32 s49, v231, 56
	s_addc_u32 s7, s59, s5
	v_cmp_gt_i32_e64 s[46:47], s0, v102
	s_movk_i32 s0, 0x2c0
	v_readlane_b32 s50, v231, 57
	v_readlane_b32 s51, v231, 58
	s_add_u32 s4, s84, s4
	v_cmp_gt_i32_e64 s[48:49], s0, v102
	s_movk_i32 s0, 0x1c0
	v_readlane_b32 s52, v231, 59
	v_readlane_b32 s53, v231, 60
	v_readlane_b32 s56, v231, 63
	v_readlane_b32 s57, v230, 0
	s_addc_u32 s5, s85, s5
	v_lshlrev_b32_e32 v2, 13, v101
	v_cmp_gt_i32_e64 s[50:51], s0, v102
	s_movk_i32 s0, 0xc0
	v_lshl_add_u64 v[70:71], s[6:7], 0, v[148:149]
	v_lshl_add_u64 v[72:73], s[4:5], 0, v[148:149]
	v_lshlrev_b32_e32 v144, 3, v101
	v_lshl_add_u64 v[134:135], v[66:67], 2, s[56:57]
	v_subrev_u32_e32 v158, 30, v6
	v_subrev_u32_e32 v160, 30, v4
	v_subrev_u32_e32 v184, 30, v182
	v_subrev_u32_e32 v186, 30, v181
	v_subrev_u32_e32 v188, 30, v180
	v_subrev_u32_e32 v190, 30, v179
	v_subrev_u32_e32 v192, 30, v178
	v_add_u32_e32 v193, 0xfffef200, v3
	v_subrev_u32_e32 v194, 30, v99
	v_add_u32_e32 v195, v148, v2
	v_lshlrev_b32_e32 v148, 1, v100
	s_lshl_b32 s64, s63, 5
	s_lshl_b32 s65, s3, 5
	s_mul_i32 s66, s63, 0x12000
	v_cmp_gt_i32_e64 s[52:53], s0, v102
	s_branch .LBB0_178
